# scan pass 2 runs inside the attention phase (no grid barrier between them; first-dispatched workgroup of each CU scans before its attention items, its partner after); scan pass 1 in the gate-GEMM epil
# speedup vs baseline: 1.0179x; 1.0163x over previous
; #define FRESH_TID() int tid = threadIdx.x; asm volatile("" : "+v"(tid)); const int wid = tid >> 6; (void)wid;
; __global__ void __launch_bounds__(256, 2) fwd_megakernel(Params p) {
;     ...
;   xcd_barrier(p.bar, xcc, xb_st);
;   {
;     FRESH_TID();
;   {
;     const int n_attn = 1024, n_s1 = B_ * NCH;
;     if (nb == 512) {
;       const int x = bid & 7, l = bid >> 3, bg = 2 * x + (l & 1), k = l >> 1;
;       attn_item(p, (k << 4) | bg, smem);
;       attn_item(p, ((63 - k) << 4) | bg, smem);
;       ph_scan1(p, bid);
.LBB0_574:
	s_or_b64 exec, exec, s[0:1]
	s_barrier
	v_readlane_b32 s2, v254, 0
	s_nop 3
	s_cmp_lt_u32 s2, 0x100
	s_cbranch_scc1 .Lp6_entry
.Lp5_resume:
	v_readlane_b32 s76, v255, 9
	v_mov_b32_e32 v1, v0
	s_cmpk_eq_i32 s92, 0x200
	s_mov_b64 s[0:1], -1
	v_readlane_b32 s78, v255, 11
	v_readlane_b32 s79, v255, 12
	v_readlane_b32 s80, v255, 13
	v_readlane_b32 s81, v255, 14
	v_readlane_b32 s82, v255, 15
	v_readlane_b32 s83, v255, 16
	v_readlane_b32 s84, v255, 17
	v_readlane_b32 s85, v255, 18
	v_readlane_b32 s86, v255, 19
	v_readlane_b32 s87, v255, 20
	v_readlane_b32 s88, v255, 21
	v_readlane_b32 s89, v255, 22
	v_readlane_b32 s90, v255, 23
	v_readlane_b32 s91, v255, 24
	s_waitcnt lgkmcnt(0)
	s_barrier
	v_readlane_b32 s77, v255, 10
	s_cbranch_scc1 .LBB0_702
	s_cmpk_gt_i32 s94, 0x5ff
	s_cbranch_scc1 .LBB0_701
	v_readlane_b32 s0, v254, 0
	s_mov_b32 s2, s0
	s_lshl_b32 s0, s0, 5
	s_add_i32 s36, s0, 0xffff8000
	s_lshl_b32 s46, s92, 5
	s_lshl_b32 s74, s2, 1
	s_lshl_b32 s75, s92, 1
	s_bitcmp1_b32 s2, 0
	s_cselect_b64 s[38:39], -1, 0
	s_bitcmp1_b32 s92, 0
	v_mbcnt_lo_u32_b32 v2, -1, 0
	s_cselect_b64 s[40:41], -1, 0
	s_mov_b32 s43, 0
	s_movk_i32 s47, 0x1000
	s_movk_i32 s94, 0x2000
	s_movk_i32 s95, 0x4000
	s_movk_i32 s96, 0x6000
	s_movk_i32 s97, 0x7000
	s_movk_i32 s14, 0x2500
	v_mov_b32_e32 v163, 0
	s_movk_i32 s15, 0x110
	s_mov_b32 s35, 0xc2fc0000
	v_mov_b32_e32 v1, 0x11080
	v_mov_b32_e32 v198, 0x11000
	v_mbcnt_hi_u32_b32 v199, -1, v2
	v_mov_b32_e32 v201, 0x5500
	v_mov_b32_e32 v202, 0x6600
	v_mov_b32_e32 v203, 0x7700
	v_mov_b32_e32 v204, 0xff800000
	v_mov_b32_e32 v205, 0x42800000
	v_not_b32_e32 v206, 63
	s_mov_b32 s4, s2
	s_mov_b32 s5, s2
	v_readlane_b32 s1, v254, 1
	s_branch .LBB0_578

; DEV int ltid() { int t = threadIdx.x; asm volatile("" : "+v"(t)); return t; }
; #define FRESH_TID() int tid = threadIdx.x; asm volatile("" : "+v"(tid)); const int wid = tid >> 6; (void)wid;
; DEV void ph_scan2(const Params& p, int item) {
;   const int b = item / NCH, c = item % NCH, ch = ltid() * 4;
;   float H[4] = {0.f, 0.f, 0.f, 0.f};
;   for (int c2 = 0; c2 < c; ++c2) {
;     float4 a = *(const float4*)(p.csA + (size_t)(b * NCH + c2) * 1024 + ch);
;     float4 hh = *(const float4*)(p.csH + (size_t)(b * NCH + c2) * 1024 + ch);
;     H[0] = a.x * H[0] + hh.x; H[1] = a.y * H[1] + hh.y; H[2] = a.z * H[2] + hh.z; H[3] = a.w * H[3] + hh.w;
;   }
;   const size_t row0 = (size_t)(b * S_ + c * CHL);
; #pragma unroll 8
; __global__ void __launch_bounds__(256, 2) fwd_megakernel(Params p) {
;     ...
;   xcd_barrier(p.bar, xcc, xb_st);
;   {
;     FRESH_TID();
;   for (int it = bid; it < B_ * NCH; it += nb) ph_scan2(p, it);
.LBB0_942:
	s_mov_b64 exec, -1
	v_readlane_b32 s2, v254, 0
	s_nop 3
	s_cmp_lt_u32 s2, 0x100
	s_cbranch_scc1 .LBB0_1132
	s_branch .Lp6_entry
.LBB0_994:
	s_mov_b64 exec, -1
.Lp6_entry:
	v_mov_b32_e32 v1, v0
	s_cmpk_gt_i32 s94, 0x1ff
	s_waitcnt lgkmcnt(0)
	s_barrier
	s_cbranch_scc1 .LBB0_1132
	s_mov_b64 exec, -1
	v_lshlrev_b32_e32 v1, 4, v0
	v_lshlrev_b32_e32 v2, 3, v0
	v_mov_b32_e32 v8, 0x3ba10414
	v_mov_b32_e32 v9, 0xb9c68948
	v_mov_b32_e32 v3, 0x7f800000
	s_mov_b32 s72, 0x378e98ab
	s_mov_b32 s73, 0x3b7cd369
	s_mov_b32 s74, 0xbcc618b2
	s_mov_b32 s75, 0x3dda74e4
	s_mov_b32 s76, 0x3f228afd
	s_mov_b32 s77, 0x3e03c728
	s_mov_b32 s78, 0xbfb8aa3b
	s_mov_b32 s79, 0x42ce8ed0
	s_mov_b32 s80, 0xc2b17218
	s_brev_b32 s81, -2
	s_mov_b32 s50, s94

; DEV unsigned pack2(float a, float b) { float2v v = {a, b}; return __builtin_bit_cast(unsigned, __builtin_convertvector(v, bf16x2v)); }
; DEV float bflo(unsigned u) { return __uint_as_float(u << 16); }
; DEV float bfhi(unsigned u) { return __uint_as_float(u & 0xffff0000u); }
; DEV float gelu_exact(float v) { return 0.5f * v * (1.f + erff(v * 0.7071067811865476f)); }
; DEV void ph_scan2(const Params& p, int item) {
;     ...
;   for (int t = 0; t < CHL; ++t) {
;     float4 a = *(const float4*)(p.a_arr + (row0 + t) * 1024 + ch);
;     float4 bb = *(const float4*)(p.b_arr + (row0 + t) * 1024 + ch);
;     u32x2 xg = *(const u32x2*)(p.z + (row0 + t) * ZLD + CXG + ch);
;     H[0] = a.x * H[0] + bb.x; H[1] = a.y * H[1] + bb.y; H[2] = a.z * H[2] + bb.z; H[3] = a.w * H[3] + bb.w;
;     u32x2 pk;
;     pk[0] = pack2(gelu_exact(bflo(xg[0])) * H[0], gelu_exact(bfhi(xg[0])) * H[1]);
;     pk[1] = pack2(gelu_exact(bflo(xg[1])) * H[2], gelu_exact(bfhi(xg[1])) * H[3]);
;     *(u32x2*)(p.orn + (row0 + t) * 1024 + ch) = pk;
;   }
.Lsc_main:
	global_load_dwordx4 v[80:83], v1, s[2:3]
	global_load_dwordx4 v[84:87], v1, s[4:5]
	global_load_dwordx2 v[88:89], v2, s[6:7]
	s_add_u32 s2, s2, 0x1000
	s_addc_u32 s3, s3, 0
	s_add_u32 s4, s4, 0x1000
	s_addc_u32 s5, s5, 0
	s_add_u32 s6, s6, 0x2500
	s_addc_u32 s7, s7, 0
	global_load_dwordx4 v[90:93], v1, s[2:3]
	global_load_dwordx4 v[94:97], v1, s[4:5]
	global_load_dwordx2 v[98:99], v2, s[6:7]
	s_add_u32 s2, s2, 0x1000
	s_addc_u32 s3, s3, 0
	s_add_u32 s4, s4, 0x1000
	s_addc_u32 s5, s5, 0
	s_add_u32 s6, s6, 0x2500
	s_addc_u32 s7, s7, 0
	global_load_dwordx4 v[100:103], v1, s[2:3]
	global_load_dwordx4 v[104:107], v1, s[4:5]
	global_load_dwordx2 v[108:109], v2, s[6:7]
	s_add_u32 s2, s2, 0x1000
	s_addc_u32 s3, s3, 0
	s_add_u32 s4, s4, 0x1000
	s_addc_u32 s5, s5, 0
	s_add_u32 s6, s6, 0x2500
	s_addc_u32 s7, s7, 0
	global_load_dwordx4 v[110:113], v1, s[2:3]
	global_load_dwordx4 v[114:117], v1, s[4:5]
	global_load_dwordx2 v[118:119], v2, s[6:7]
	s_add_u32 s2, s2, 0x1000
	s_addc_u32 s3, s3, 0
	s_add_u32 s4, s4, 0x1000
	s_addc_u32 s5, s5, 0
	s_add_u32 s6, s6, 0x2500
	s_addc_u32 s7, s7, 0
	global_load_dwordx4 v[120:123], v1, s[2:3]
	global_load_dwordx4 v[124:127], v1, s[4:5]
	global_load_dwordx2 v[128:129], v2, s[6:7]
	s_add_u32 s2, s2, 0x1000
	s_addc_u32 s3, s3, 0
	s_add_u32 s4, s4, 0x1000
	s_addc_u32 s5, s5, 0
	s_add_u32 s6, s6, 0x2500
	s_addc_u32 s7, s7, 0
	global_load_dwordx4 v[130:133], v1, s[2:3]
	global_load_dwordx4 v[134:137], v1, s[4:5]
	global_load_dwordx2 v[138:139], v2, s[6:7]
	s_add_u32 s2, s2, 0x1000
	s_addc_u32 s3, s3, 0
	s_add_u32 s4, s4, 0x1000
	s_addc_u32 s5, s5, 0
	s_add_u32 s6, s6, 0x2500
	s_addc_u32 s7, s7, 0
	global_load_dwordx4 v[140:143], v1, s[2:3]
	global_load_dwordx4 v[144:147], v1, s[4:5]
	global_load_dwordx2 v[148:149], v2, s[6:7]
	s_add_u32 s2, s2, 0x1000
	s_addc_u32 s3, s3, 0
	s_add_u32 s4, s4, 0x1000
	s_addc_u32 s5, s5, 0
	s_add_u32 s6, s6, 0x2500
	s_addc_u32 s7, s7, 0
	global_load_dwordx4 v[150:153], v1, s[2:3]
	global_load_dwordx4 v[154:157], v1, s[4:5]
	global_load_dwordx2 v[158:159], v2, s[6:7]
	s_add_u32 s2, s2, 0x1000
	s_addc_u32 s3, s3, 0
	s_add_u32 s4, s4, 0x1000
	s_addc_u32 s5, s5, 0
	s_add_u32 s6, s6, 0x2500
	s_addc_u32 s7, s7, 0
	s_waitcnt vmcnt(21)
	v_fma_f32 v4, v80, v4, v84
	v_fma_f32 v5, v81, v5, v85
	v_fma_f32 v6, v82, v6, v86
	v_fma_f32 v7, v83, v7, v87
	v_lshlrev_b32_e32 v168, 16, v88
	v_and_b32_e32 v169, 0xffff0000, v88
	v_lshlrev_b32_e32 v170, 16, v89
	v_and_b32_e32 v171, 0xffff0000, v89
	v_mul_f32_e32 v160, 0x3f3504f3, v168
	v_mul_f32_e32 v161, v160, v160
	v_fmamk_f32 v162, v161, 0xba1345e1, v8
	v_fmaak_f32 v162, v161, v162, 0xbcdac9b8
	v_fmaak_f32 v162, v161, v162, 0x3de703be
	v_fmaak_f32 v162, v161, v162, 0xbec09330
	v_fmaak_f32 v161, v161, v162, 0x3e0375d0
	v_fma_f32 v165, |v160|, v161, |v160|
	v_fma_f32 v161, |v160|, s72, v9
	v_fma_f32 v161, |v160|, v161, s73
	v_fma_f32 v161, |v160|, v161, s74
	v_fma_f32 v161, |v160|, v161, s75
	v_fma_f32 v161, |v160|, v161, s76
	v_fma_f32 v161, |v160|, v161, s77
	v_fma_f32 v161, |v160|, v161, |v160|
	v_mul_f32_e32 v162, 0xbfb8aa3b, v161
	v_fma_f32 v163, v161, s78, -v162
	v_rndne_f32_e32 v164, v162
	v_fmac_f32_e32 v163, 0xb2a5705f, v161
	v_sub_f32_e32 v162, v162, v164
	v_add_f32_e32 v162, v162, v163
	v_cvt_i32_f32_e32 v163, v164
	v_exp_f32_e32 v162, v162
	v_cmp_nlt_f32_e32 vcc, s79, v161
	v_ldexp_f32 v162, v162, v163
	s_nop 0
	v_cndmask_b32_e32 v162, 0, v162, vcc
	v_cmp_ngt_f32_e32 vcc, s80, v161
	s_nop 1
	v_cndmask_b32_e32 v161, v3, v162, vcc
	v_sub_f32_e32 v166, 1.0, v161
	v_cmp_lt_f32_e64 vcc, |v160|, 1.0
	s_nop 1
	v_cndmask_b32_e32 v165, v166, v165, vcc
	v_bfi_b32 v165, s81, v165, v160
	v_mul_f32_e32 v161, 0.5, v168
	v_add_f32_e32 v165, 1.0, v165
	v_mul_f32_e32 v161, v161, v165
	v_mul_f32_e32 v176, v161, v4
	v_mul_f32_e32 v160, 0x3f3504f3, v169
	v_mul_f32_e32 v161, v160, v160
	v_fmamk_f32 v162, v161, 0xba1345e1, v8
	v_fmaak_f32 v162, v161, v162, 0xbcdac9b8
	v_fmaak_f32 v162, v161, v162, 0x3de703be
	v_fmaak_f32 v162, v161, v162, 0xbec09330
	v_fmaak_f32 v161, v161, v162, 0x3e0375d0
	v_fma_f32 v165, |v160|, v161, |v160|
	v_fma_f32 v161, |v160|, s72, v9
	v_fma_f32 v161, |v160|, v161, s73
	v_fma_f32 v161, |v160|, v161, s74
	v_fma_f32 v161, |v160|, v161, s75
	v_fma_f32 v161, |v160|, v161, s76
	v_fma_f32 v161, |v160|, v161, s77
	v_fma_f32 v161, |v160|, v161, |v160|
	v_mul_f32_e32 v162, 0xbfb8aa3b, v161
	v_fma_f32 v163, v161, s78, -v162
	v_rndne_f32_e32 v164, v162
	v_fmac_f32_e32 v163, 0xb2a5705f, v161
	v_sub_f32_e32 v162, v162, v164
	v_add_f32_e32 v162, v162, v163
	v_cvt_i32_f32_e32 v163, v164
	v_exp_f32_e32 v162, v162
	v_cmp_nlt_f32_e32 vcc, s79, v161
	v_ldexp_f32 v162, v162, v163
	s_nop 0
	v_cndmask_b32_e32 v162, 0, v162, vcc
	v_cmp_ngt_f32_e32 vcc, s80, v161
	s_nop 1
	v_cndmask_b32_e32 v161, v3, v162, vcc
	v_sub_f32_e32 v166, 1.0, v161
	v_cmp_lt_f32_e64 vcc, |v160|, 1.0
	s_nop 1
	v_cndmask_b32_e32 v165, v166, v165, vcc
	v_bfi_b32 v165, s81, v165, v160
	v_mul_f32_e32 v161, 0.5, v169
	v_add_f32_e32 v165, 1.0, v165
	v_mul_f32_e32 v161, v161, v165
	v_mul_f32_e32 v177, v161, v5
	v_mul_f32_e32 v160, 0x3f3504f3, v170
	v_mul_f32_e32 v161, v160, v160
	v_fmamk_f32 v162, v161, 0xba1345e1, v8
	v_fmaak_f32 v162, v161, v162, 0xbcdac9b8
	v_fmaak_f32 v162, v161, v162, 0x3de703be
	v_fmaak_f32 v162, v161, v162, 0xbec09330
	v_fmaak_f32 v161, v161, v162, 0x3e0375d0
	v_fma_f32 v165, |v160|, v161, |v160|
	v_fma_f32 v161, |v160|, s72, v9
	v_fma_f32 v161, |v160|, v161, s73
	v_fma_f32 v161, |v160|, v161, s74
	v_fma_f32 v161, |v160|, v161, s75
	v_fma_f32 v161, |v160|, v161, s76
	v_fma_f32 v161, |v160|, v161, s77
	v_fma_f32 v161, |v160|, v161, |v160|
	v_mul_f32_e32 v162, 0xbfb8aa3b, v161
; DEV unsigned pack2(float a, float b) { float2v v = {a, b}; return __builtin_bit_cast(unsigned, __builtin_convertvector(v, bf16x2v)); }
; DEV float bflo(unsigned u) { return __uint_as_float(u << 16); }
; DEV float bfhi(unsigned u) { return __uint_as_float(u & 0xffff0000u); }
; DEV float gelu_exact(float v) { return 0.5f * v * (1.f + erff(v * 0.7071067811865476f)); }
; DEV void ph_scan2(const Params& p, int item) {
;     ...
;   for (int t = 0; t < CHL; ++t) {
;     float4 a = *(const float4*)(p.a_arr + (row0 + t) * 1024 + ch);
;     float4 bb = *(const float4*)(p.b_arr + (row0 + t) * 1024 + ch);
;     u32x2 xg = *(const u32x2*)(p.z + (row0 + t) * ZLD + CXG + ch);
;     H[0] = a.x * H[0] + bb.x; H[1] = a.y * H[1] + bb.y; H[2] = a.z * H[2] + bb.z; H[3] = a.w * H[3] + bb.w;
;     u32x2 pk;
;     pk[0] = pack2(gelu_exact(bflo(xg[0])) * H[0], gelu_exact(bfhi(xg[0])) * H[1]);
;     pk[1] = pack2(gelu_exact(bflo(xg[1])) * H[2], gelu_exact(bfhi(xg[1])) * H[3]);
;     *(u32x2*)(p.orn + (row0 + t) * 1024 + ch) = pk;
;   }
	v_fma_f32 v163, v161, s78, -v162
	v_rndne_f32_e32 v164, v162
	v_fmac_f32_e32 v163, 0xb2a5705f, v161
	v_sub_f32_e32 v162, v162, v164
	v_add_f32_e32 v162, v162, v163
	v_cvt_i32_f32_e32 v163, v164
	v_exp_f32_e32 v162, v162
	v_cmp_nlt_f32_e32 vcc, s79, v161
	v_ldexp_f32 v162, v162, v163
	s_nop 0
	v_cndmask_b32_e32 v162, 0, v162, vcc
	v_cmp_ngt_f32_e32 vcc, s80, v161
	s_nop 1
	v_cndmask_b32_e32 v161, v3, v162, vcc
	v_sub_f32_e32 v166, 1.0, v161
	v_cmp_lt_f32_e64 vcc, |v160|, 1.0
	s_nop 1
	v_cndmask_b32_e32 v165, v166, v165, vcc
	v_bfi_b32 v165, s81, v165, v160
	v_mul_f32_e32 v161, 0.5, v170
	v_add_f32_e32 v165, 1.0, v165
	v_mul_f32_e32 v161, v161, v165
	v_mul_f32_e32 v178, v161, v6
	v_mul_f32_e32 v160, 0x3f3504f3, v171
	v_mul_f32_e32 v161, v160, v160
	v_fmamk_f32 v162, v161, 0xba1345e1, v8
	v_fmaak_f32 v162, v161, v162, 0xbcdac9b8
	v_fmaak_f32 v162, v161, v162, 0x3de703be
	v_fmaak_f32 v162, v161, v162, 0xbec09330
	v_fmaak_f32 v161, v161, v162, 0x3e0375d0
	v_fma_f32 v165, |v160|, v161, |v160|
	v_fma_f32 v161, |v160|, s72, v9
	v_fma_f32 v161, |v160|, v161, s73
	v_fma_f32 v161, |v160|, v161, s74
	v_fma_f32 v161, |v160|, v161, s75
	v_fma_f32 v161, |v160|, v161, s76
	v_fma_f32 v161, |v160|, v161, s77
	v_fma_f32 v161, |v160|, v161, |v160|
	v_mul_f32_e32 v162, 0xbfb8aa3b, v161
	v_fma_f32 v163, v161, s78, -v162
	v_rndne_f32_e32 v164, v162
	v_fmac_f32_e32 v163, 0xb2a5705f, v161
	v_sub_f32_e32 v162, v162, v164
	v_add_f32_e32 v162, v162, v163
	v_cvt_i32_f32_e32 v163, v164
	v_exp_f32_e32 v162, v162
	v_cmp_nlt_f32_e32 vcc, s79, v161
	v_ldexp_f32 v162, v162, v163
	s_nop 0
	v_cndmask_b32_e32 v162, 0, v162, vcc
	v_cmp_ngt_f32_e32 vcc, s80, v161
	s_nop 1
	v_cndmask_b32_e32 v161, v3, v162, vcc
	v_sub_f32_e32 v166, 1.0, v161
	v_cmp_lt_f32_e64 vcc, |v160|, 1.0
	s_nop 1
	v_cndmask_b32_e32 v165, v166, v165, vcc
	v_bfi_b32 v165, s81, v165, v160
	v_mul_f32_e32 v161, 0.5, v171
	v_add_f32_e32 v165, 1.0, v165
	v_mul_f32_e32 v161, v161, v165
	v_mul_f32_e32 v179, v161, v7
	v_cvt_pk_bf16_f32 v180, v176, v177
	v_cvt_pk_bf16_f32 v181, v178, v179
	global_store_dwordx2 v2, v[180:181], s[34:35]
	s_add_u32 s34, s34, 0x800
	s_addc_u32 s35, s35, 0
	s_waitcnt vmcnt(19)
	v_fma_f32 v4, v90, v4, v94
	v_fma_f32 v5, v91, v5, v95
	v_fma_f32 v6, v92, v6, v96
	v_fma_f32 v7, v93, v7, v97
	v_lshlrev_b32_e32 v168, 16, v98
	v_and_b32_e32 v169, 0xffff0000, v98
	v_lshlrev_b32_e32 v170, 16, v99
	v_and_b32_e32 v171, 0xffff0000, v99
	v_mul_f32_e32 v160, 0x3f3504f3, v168
	v_mul_f32_e32 v161, v160, v160
	v_fmamk_f32 v162, v161, 0xba1345e1, v8
	v_fmaak_f32 v162, v161, v162, 0xbcdac9b8
	v_fmaak_f32 v162, v161, v162, 0x3de703be
	v_fmaak_f32 v162, v161, v162, 0xbec09330
	v_fmaak_f32 v161, v161, v162, 0x3e0375d0
	v_fma_f32 v165, |v160|, v161, |v160|
	v_fma_f32 v161, |v160|, s72, v9
	v_fma_f32 v161, |v160|, v161, s73
	v_fma_f32 v161, |v160|, v161, s74
	v_fma_f32 v161, |v160|, v161, s75
	v_fma_f32 v161, |v160|, v161, s76
	v_fma_f32 v161, |v160|, v161, s77
	v_fma_f32 v161, |v160|, v161, |v160|
	v_mul_f32_e32 v162, 0xbfb8aa3b, v161
	v_fma_f32 v163, v161, s78, -v162
	v_rndne_f32_e32 v164, v162
	v_fmac_f32_e32 v163, 0xb2a5705f, v161
	v_sub_f32_e32 v162, v162, v164
	v_add_f32_e32 v162, v162, v163
	v_cvt_i32_f32_e32 v163, v164
	v_exp_f32_e32 v162, v162
	v_cmp_nlt_f32_e32 vcc, s79, v161
	v_ldexp_f32 v162, v162, v163
	s_nop 0
	v_cndmask_b32_e32 v162, 0, v162, vcc
	v_cmp_ngt_f32_e32 vcc, s80, v161
	s_nop 1
	v_cndmask_b32_e32 v161, v3, v162, vcc
	v_sub_f32_e32 v166, 1.0, v161
	v_cmp_lt_f32_e64 vcc, |v160|, 1.0
	s_nop 1
	v_cndmask_b32_e32 v165, v166, v165, vcc
	v_bfi_b32 v165, s81, v165, v160
	v_mul_f32_e32 v161, 0.5, v168
	v_add_f32_e32 v165, 1.0, v165
	v_mul_f32_e32 v161, v161, v165
	v_mul_f32_e32 v176, v161, v4
	v_mul_f32_e32 v160, 0x3f3504f3, v169
	v_mul_f32_e32 v161, v160, v160
	v_fmamk_f32 v162, v161, 0xba1345e1, v8
	v_fmaak_f32 v162, v161, v162, 0xbcdac9b8
	v_fmaak_f32 v162, v161, v162, 0x3de703be
	v_fmaak_f32 v162, v161, v162, 0xbec09330
	v_fmaak_f32 v161, v161, v162, 0x3e0375d0
	v_fma_f32 v165, |v160|, v161, |v160|
	v_fma_f32 v161, |v160|, s72, v9
	v_fma_f32 v161, |v160|, v161, s73
	v_fma_f32 v161, |v160|, v161, s74
	v_fma_f32 v161, |v160|, v161, s75
	v_fma_f32 v161, |v160|, v161, s76
	v_fma_f32 v161, |v160|, v161, s77
	v_fma_f32 v161, |v160|, v161, |v160|
	v_mul_f32_e32 v162, 0xbfb8aa3b, v161
	v_fma_f32 v163, v161, s78, -v162
	v_rndne_f32_e32 v164, v162
	v_fmac_f32_e32 v163, 0xb2a5705f, v161
	v_sub_f32_e32 v162, v162, v164
	v_add_f32_e32 v162, v162, v163
	v_cvt_i32_f32_e32 v163, v164
	v_exp_f32_e32 v162, v162
	v_cmp_nlt_f32_e32 vcc, s79, v161
	v_ldexp_f32 v162, v162, v163
	s_nop 0
	v_cndmask_b32_e32 v162, 0, v162, vcc
	v_cmp_ngt_f32_e32 vcc, s80, v161
	s_nop 1
	v_cndmask_b32_e32 v161, v3, v162, vcc
	v_sub_f32_e32 v166, 1.0, v161
	v_cmp_lt_f32_e64 vcc, |v160|, 1.0
	s_nop 1
	v_cndmask_b32_e32 v165, v166, v165, vcc
	v_bfi_b32 v165, s81, v165, v160
	v_mul_f32_e32 v161, 0.5, v169
	v_add_f32_e32 v165, 1.0, v165
	v_mul_f32_e32 v161, v161, v165
	v_mul_f32_e32 v177, v161, v5
	v_mul_f32_e32 v160, 0x3f3504f3, v170
	v_mul_f32_e32 v161, v160, v160
	v_fmamk_f32 v162, v161, 0xba1345e1, v8
	v_fmaak_f32 v162, v161, v162, 0xbcdac9b8
	v_fmaak_f32 v162, v161, v162, 0x3de703be
	v_fmaak_f32 v162, v161, v162, 0xbec09330
	v_fmaak_f32 v161, v161, v162, 0x3e0375d0
	v_fma_f32 v165, |v160|, v161, |v160|
	v_fma_f32 v161, |v160|, s72, v9
	v_fma_f32 v161, |v160|, v161, s73
	v_fma_f32 v161, |v160|, v161, s74
	v_fma_f32 v161, |v160|, v161, s75
	v_fma_f32 v161, |v160|, v161, s76
	v_fma_f32 v161, |v160|, v161, s77
	v_fma_f32 v161, |v160|, v161, |v160|
	v_mul_f32_e32 v162, 0xbfb8aa3b, v161
	v_fma_f32 v163, v161, s78, -v162
	v_rndne_f32_e32 v164, v162
; DEV unsigned pack2(float a, float b) { float2v v = {a, b}; return __builtin_bit_cast(unsigned, __builtin_convertvector(v, bf16x2v)); }
; DEV float bflo(unsigned u) { return __uint_as_float(u << 16); }
; DEV float bfhi(unsigned u) { return __uint_as_float(u & 0xffff0000u); }
; DEV float gelu_exact(float v) { return 0.5f * v * (1.f + erff(v * 0.7071067811865476f)); }
; DEV void ph_scan2(const Params& p, int item) {
;     ...
;   for (int t = 0; t < CHL; ++t) {
;     float4 a = *(const float4*)(p.a_arr + (row0 + t) * 1024 + ch);
;     float4 bb = *(const float4*)(p.b_arr + (row0 + t) * 1024 + ch);
;     u32x2 xg = *(const u32x2*)(p.z + (row0 + t) * ZLD + CXG + ch);
;     H[0] = a.x * H[0] + bb.x; H[1] = a.y * H[1] + bb.y; H[2] = a.z * H[2] + bb.z; H[3] = a.w * H[3] + bb.w;
;     u32x2 pk;
;     pk[0] = pack2(gelu_exact(bflo(xg[0])) * H[0], gelu_exact(bfhi(xg[0])) * H[1]);
;     pk[1] = pack2(gelu_exact(bflo(xg[1])) * H[2], gelu_exact(bfhi(xg[1])) * H[3]);
;     *(u32x2*)(p.orn + (row0 + t) * 1024 + ch) = pk;
;   }
	v_fmac_f32_e32 v163, 0xb2a5705f, v161
	v_sub_f32_e32 v162, v162, v164
	v_add_f32_e32 v162, v162, v163
	v_cvt_i32_f32_e32 v163, v164
	v_exp_f32_e32 v162, v162
	v_cmp_nlt_f32_e32 vcc, s79, v161
	v_ldexp_f32 v162, v162, v163
	s_nop 0
	v_cndmask_b32_e32 v162, 0, v162, vcc
	v_cmp_ngt_f32_e32 vcc, s80, v161
	s_nop 1
	v_cndmask_b32_e32 v161, v3, v162, vcc
	v_sub_f32_e32 v166, 1.0, v161
	v_cmp_lt_f32_e64 vcc, |v160|, 1.0
	s_nop 1
	v_cndmask_b32_e32 v165, v166, v165, vcc
	v_bfi_b32 v165, s81, v165, v160
	v_mul_f32_e32 v161, 0.5, v170
	v_add_f32_e32 v165, 1.0, v165
	v_mul_f32_e32 v161, v161, v165
	v_mul_f32_e32 v178, v161, v6
	v_mul_f32_e32 v160, 0x3f3504f3, v171
	v_mul_f32_e32 v161, v160, v160
	v_fmamk_f32 v162, v161, 0xba1345e1, v8
	v_fmaak_f32 v162, v161, v162, 0xbcdac9b8
	v_fmaak_f32 v162, v161, v162, 0x3de703be
	v_fmaak_f32 v162, v161, v162, 0xbec09330
	v_fmaak_f32 v161, v161, v162, 0x3e0375d0
	v_fma_f32 v165, |v160|, v161, |v160|
	v_fma_f32 v161, |v160|, s72, v9
	v_fma_f32 v161, |v160|, v161, s73
	v_fma_f32 v161, |v160|, v161, s74
	v_fma_f32 v161, |v160|, v161, s75
	v_fma_f32 v161, |v160|, v161, s76
	v_fma_f32 v161, |v160|, v161, s77
	v_fma_f32 v161, |v160|, v161, |v160|
	v_mul_f32_e32 v162, 0xbfb8aa3b, v161
	v_fma_f32 v163, v161, s78, -v162
	v_rndne_f32_e32 v164, v162
	v_fmac_f32_e32 v163, 0xb2a5705f, v161
	v_sub_f32_e32 v162, v162, v164
	v_add_f32_e32 v162, v162, v163
	v_cvt_i32_f32_e32 v163, v164
	v_exp_f32_e32 v162, v162
	v_cmp_nlt_f32_e32 vcc, s79, v161
	v_ldexp_f32 v162, v162, v163
	s_nop 0
	v_cndmask_b32_e32 v162, 0, v162, vcc
	v_cmp_ngt_f32_e32 vcc, s80, v161
	s_nop 1
	v_cndmask_b32_e32 v161, v3, v162, vcc
	v_sub_f32_e32 v166, 1.0, v161
	v_cmp_lt_f32_e64 vcc, |v160|, 1.0
	s_nop 1
	v_cndmask_b32_e32 v165, v166, v165, vcc
	v_bfi_b32 v165, s81, v165, v160
	v_mul_f32_e32 v161, 0.5, v171
	v_add_f32_e32 v165, 1.0, v165
	v_mul_f32_e32 v161, v161, v165
	v_mul_f32_e32 v179, v161, v7
	v_cvt_pk_bf16_f32 v180, v176, v177
	v_cvt_pk_bf16_f32 v181, v178, v179
	global_store_dwordx2 v2, v[180:181], s[34:35]
	s_add_u32 s34, s34, 0x800
	s_addc_u32 s35, s35, 0
	s_waitcnt vmcnt(17)
	v_fma_f32 v4, v100, v4, v104
	v_fma_f32 v5, v101, v5, v105
	v_fma_f32 v6, v102, v6, v106
	v_fma_f32 v7, v103, v7, v107
	v_lshlrev_b32_e32 v168, 16, v108
	v_and_b32_e32 v169, 0xffff0000, v108
	v_lshlrev_b32_e32 v170, 16, v109
	v_and_b32_e32 v171, 0xffff0000, v109
	v_mul_f32_e32 v160, 0x3f3504f3, v168
	v_mul_f32_e32 v161, v160, v160
	v_fmamk_f32 v162, v161, 0xba1345e1, v8
	v_fmaak_f32 v162, v161, v162, 0xbcdac9b8
	v_fmaak_f32 v162, v161, v162, 0x3de703be
	v_fmaak_f32 v162, v161, v162, 0xbec09330
	v_fmaak_f32 v161, v161, v162, 0x3e0375d0
	v_fma_f32 v165, |v160|, v161, |v160|
	v_fma_f32 v161, |v160|, s72, v9
	v_fma_f32 v161, |v160|, v161, s73
	v_fma_f32 v161, |v160|, v161, s74
	v_fma_f32 v161, |v160|, v161, s75
	v_fma_f32 v161, |v160|, v161, s76
	v_fma_f32 v161, |v160|, v161, s77
	v_fma_f32 v161, |v160|, v161, |v160|
	v_mul_f32_e32 v162, 0xbfb8aa3b, v161
	v_fma_f32 v163, v161, s78, -v162
	v_rndne_f32_e32 v164, v162
	v_fmac_f32_e32 v163, 0xb2a5705f, v161
	v_sub_f32_e32 v162, v162, v164
	v_add_f32_e32 v162, v162, v163
	v_cvt_i32_f32_e32 v163, v164
	v_exp_f32_e32 v162, v162
	v_cmp_nlt_f32_e32 vcc, s79, v161
	v_ldexp_f32 v162, v162, v163
	s_nop 0
	v_cndmask_b32_e32 v162, 0, v162, vcc
	v_cmp_ngt_f32_e32 vcc, s80, v161
	s_nop 1
	v_cndmask_b32_e32 v161, v3, v162, vcc
	v_sub_f32_e32 v166, 1.0, v161
	v_cmp_lt_f32_e64 vcc, |v160|, 1.0
	s_nop 1
	v_cndmask_b32_e32 v165, v166, v165, vcc
	v_bfi_b32 v165, s81, v165, v160
	v_mul_f32_e32 v161, 0.5, v168
	v_add_f32_e32 v165, 1.0, v165
	v_mul_f32_e32 v161, v161, v165
	v_mul_f32_e32 v176, v161, v4
	v_mul_f32_e32 v160, 0x3f3504f3, v169
	v_mul_f32_e32 v161, v160, v160
	v_fmamk_f32 v162, v161, 0xba1345e1, v8
	v_fmaak_f32 v162, v161, v162, 0xbcdac9b8
	v_fmaak_f32 v162, v161, v162, 0x3de703be
	v_fmaak_f32 v162, v161, v162, 0xbec09330
	v_fmaak_f32 v161, v161, v162, 0x3e0375d0
	v_fma_f32 v165, |v160|, v161, |v160|
	v_fma_f32 v161, |v160|, s72, v9
	v_fma_f32 v161, |v160|, v161, s73
	v_fma_f32 v161, |v160|, v161, s74
	v_fma_f32 v161, |v160|, v161, s75
	v_fma_f32 v161, |v160|, v161, s76
	v_fma_f32 v161, |v160|, v161, s77
	v_fma_f32 v161, |v160|, v161, |v160|
	v_mul_f32_e32 v162, 0xbfb8aa3b, v161
	v_fma_f32 v163, v161, s78, -v162
	v_rndne_f32_e32 v164, v162
	v_fmac_f32_e32 v163, 0xb2a5705f, v161
	v_sub_f32_e32 v162, v162, v164
	v_add_f32_e32 v162, v162, v163
	v_cvt_i32_f32_e32 v163, v164
	v_exp_f32_e32 v162, v162
	v_cmp_nlt_f32_e32 vcc, s79, v161
	v_ldexp_f32 v162, v162, v163
	s_nop 0
	v_cndmask_b32_e32 v162, 0, v162, vcc
	v_cmp_ngt_f32_e32 vcc, s80, v161
	s_nop 1
	v_cndmask_b32_e32 v161, v3, v162, vcc
	v_sub_f32_e32 v166, 1.0, v161
	v_cmp_lt_f32_e64 vcc, |v160|, 1.0
	s_nop 1
	v_cndmask_b32_e32 v165, v166, v165, vcc
	v_bfi_b32 v165, s81, v165, v160
	v_mul_f32_e32 v161, 0.5, v169
	v_add_f32_e32 v165, 1.0, v165
	v_mul_f32_e32 v161, v161, v165
	v_mul_f32_e32 v177, v161, v5
	v_mul_f32_e32 v160, 0x3f3504f3, v170
	v_mul_f32_e32 v161, v160, v160
	v_fmamk_f32 v162, v161, 0xba1345e1, v8
	v_fmaak_f32 v162, v161, v162, 0xbcdac9b8
	v_fmaak_f32 v162, v161, v162, 0x3de703be
	v_fmaak_f32 v162, v161, v162, 0xbec09330
	v_fmaak_f32 v161, v161, v162, 0x3e0375d0
	v_fma_f32 v165, |v160|, v161, |v160|
	v_fma_f32 v161, |v160|, s72, v9
	v_fma_f32 v161, |v160|, v161, s73
	v_fma_f32 v161, |v160|, v161, s74
	v_fma_f32 v161, |v160|, v161, s75
	v_fma_f32 v161, |v160|, v161, s76
	v_fma_f32 v161, |v160|, v161, s77
	v_fma_f32 v161, |v160|, v161, |v160|
	v_mul_f32_e32 v162, 0xbfb8aa3b, v161
	v_fma_f32 v163, v161, s78, -v162
	v_rndne_f32_e32 v164, v162
	v_fmac_f32_e32 v163, 0xb2a5705f, v161
; DEV unsigned pack2(float a, float b) { float2v v = {a, b}; return __builtin_bit_cast(unsigned, __builtin_convertvector(v, bf16x2v)); }
; DEV float bflo(unsigned u) { return __uint_as_float(u << 16); }
; DEV float bfhi(unsigned u) { return __uint_as_float(u & 0xffff0000u); }
; DEV float gelu_exact(float v) { return 0.5f * v * (1.f + erff(v * 0.7071067811865476f)); }
; DEV void ph_scan2(const Params& p, int item) {
;     ...
;   for (int t = 0; t < CHL; ++t) {
;     float4 a = *(const float4*)(p.a_arr + (row0 + t) * 1024 + ch);
;     float4 bb = *(const float4*)(p.b_arr + (row0 + t) * 1024 + ch);
;     u32x2 xg = *(const u32x2*)(p.z + (row0 + t) * ZLD + CXG + ch);
;     H[0] = a.x * H[0] + bb.x; H[1] = a.y * H[1] + bb.y; H[2] = a.z * H[2] + bb.z; H[3] = a.w * H[3] + bb.w;
;     u32x2 pk;
;     pk[0] = pack2(gelu_exact(bflo(xg[0])) * H[0], gelu_exact(bfhi(xg[0])) * H[1]);
;     pk[1] = pack2(gelu_exact(bflo(xg[1])) * H[2], gelu_exact(bfhi(xg[1])) * H[3]);
;     *(u32x2*)(p.orn + (row0 + t) * 1024 + ch) = pk;
;   }
	v_sub_f32_e32 v162, v162, v164
	v_add_f32_e32 v162, v162, v163
	v_cvt_i32_f32_e32 v163, v164
	v_exp_f32_e32 v162, v162
	v_cmp_nlt_f32_e32 vcc, s79, v161
	v_ldexp_f32 v162, v162, v163
	s_nop 0
	v_cndmask_b32_e32 v162, 0, v162, vcc
	v_cmp_ngt_f32_e32 vcc, s80, v161
	s_nop 1
	v_cndmask_b32_e32 v161, v3, v162, vcc
	v_sub_f32_e32 v166, 1.0, v161
	v_cmp_lt_f32_e64 vcc, |v160|, 1.0
	s_nop 1
	v_cndmask_b32_e32 v165, v166, v165, vcc
	v_bfi_b32 v165, s81, v165, v160
	v_mul_f32_e32 v161, 0.5, v170
	v_add_f32_e32 v165, 1.0, v165
	v_mul_f32_e32 v161, v161, v165
	v_mul_f32_e32 v178, v161, v6
	v_mul_f32_e32 v160, 0x3f3504f3, v171
	v_mul_f32_e32 v161, v160, v160
	v_fmamk_f32 v162, v161, 0xba1345e1, v8
	v_fmaak_f32 v162, v161, v162, 0xbcdac9b8
	v_fmaak_f32 v162, v161, v162, 0x3de703be
	v_fmaak_f32 v162, v161, v162, 0xbec09330
	v_fmaak_f32 v161, v161, v162, 0x3e0375d0
	v_fma_f32 v165, |v160|, v161, |v160|
	v_fma_f32 v161, |v160|, s72, v9
	v_fma_f32 v161, |v160|, v161, s73
	v_fma_f32 v161, |v160|, v161, s74
	v_fma_f32 v161, |v160|, v161, s75
	v_fma_f32 v161, |v160|, v161, s76
	v_fma_f32 v161, |v160|, v161, s77
	v_fma_f32 v161, |v160|, v161, |v160|
	v_mul_f32_e32 v162, 0xbfb8aa3b, v161
	v_fma_f32 v163, v161, s78, -v162
	v_rndne_f32_e32 v164, v162
	v_fmac_f32_e32 v163, 0xb2a5705f, v161
	v_sub_f32_e32 v162, v162, v164
	v_add_f32_e32 v162, v162, v163
	v_cvt_i32_f32_e32 v163, v164
	v_exp_f32_e32 v162, v162
	v_cmp_nlt_f32_e32 vcc, s79, v161
	v_ldexp_f32 v162, v162, v163
	s_nop 0
	v_cndmask_b32_e32 v162, 0, v162, vcc
	v_cmp_ngt_f32_e32 vcc, s80, v161
	s_nop 1
	v_cndmask_b32_e32 v161, v3, v162, vcc
	v_sub_f32_e32 v166, 1.0, v161
	v_cmp_lt_f32_e64 vcc, |v160|, 1.0
	s_nop 1
	v_cndmask_b32_e32 v165, v166, v165, vcc
	v_bfi_b32 v165, s81, v165, v160
	v_mul_f32_e32 v161, 0.5, v171
	v_add_f32_e32 v165, 1.0, v165
	v_mul_f32_e32 v161, v161, v165
	v_mul_f32_e32 v179, v161, v7
	v_cvt_pk_bf16_f32 v180, v176, v177
	v_cvt_pk_bf16_f32 v181, v178, v179
	global_store_dwordx2 v2, v[180:181], s[34:35]
	s_add_u32 s34, s34, 0x800
	s_addc_u32 s35, s35, 0
	s_waitcnt vmcnt(15)
	v_fma_f32 v4, v110, v4, v114
	v_fma_f32 v5, v111, v5, v115
	v_fma_f32 v6, v112, v6, v116
	v_fma_f32 v7, v113, v7, v117
	v_lshlrev_b32_e32 v168, 16, v118
	v_and_b32_e32 v169, 0xffff0000, v118
	v_lshlrev_b32_e32 v170, 16, v119
	v_and_b32_e32 v171, 0xffff0000, v119
	v_mul_f32_e32 v160, 0x3f3504f3, v168
	v_mul_f32_e32 v161, v160, v160
	v_fmamk_f32 v162, v161, 0xba1345e1, v8
	v_fmaak_f32 v162, v161, v162, 0xbcdac9b8
	v_fmaak_f32 v162, v161, v162, 0x3de703be
	v_fmaak_f32 v162, v161, v162, 0xbec09330
	v_fmaak_f32 v161, v161, v162, 0x3e0375d0
	v_fma_f32 v165, |v160|, v161, |v160|
	v_fma_f32 v161, |v160|, s72, v9
	v_fma_f32 v161, |v160|, v161, s73
	v_fma_f32 v161, |v160|, v161, s74
	v_fma_f32 v161, |v160|, v161, s75
	v_fma_f32 v161, |v160|, v161, s76
	v_fma_f32 v161, |v160|, v161, s77
	v_fma_f32 v161, |v160|, v161, |v160|
	v_mul_f32_e32 v162, 0xbfb8aa3b, v161
	v_fma_f32 v163, v161, s78, -v162
	v_rndne_f32_e32 v164, v162
	v_fmac_f32_e32 v163, 0xb2a5705f, v161
	v_sub_f32_e32 v162, v162, v164
	v_add_f32_e32 v162, v162, v163
	v_cvt_i32_f32_e32 v163, v164
	v_exp_f32_e32 v162, v162
	v_cmp_nlt_f32_e32 vcc, s79, v161
	v_ldexp_f32 v162, v162, v163
	s_nop 0
	v_cndmask_b32_e32 v162, 0, v162, vcc
	v_cmp_ngt_f32_e32 vcc, s80, v161
	s_nop 1
	v_cndmask_b32_e32 v161, v3, v162, vcc
	v_sub_f32_e32 v166, 1.0, v161
	v_cmp_lt_f32_e64 vcc, |v160|, 1.0
	s_nop 1
	v_cndmask_b32_e32 v165, v166, v165, vcc
	v_bfi_b32 v165, s81, v165, v160
	v_mul_f32_e32 v161, 0.5, v168
	v_add_f32_e32 v165, 1.0, v165
	v_mul_f32_e32 v161, v161, v165
	v_mul_f32_e32 v176, v161, v4
	v_mul_f32_e32 v160, 0x3f3504f3, v169
	v_mul_f32_e32 v161, v160, v160
	v_fmamk_f32 v162, v161, 0xba1345e1, v8
	v_fmaak_f32 v162, v161, v162, 0xbcdac9b8
	v_fmaak_f32 v162, v161, v162, 0x3de703be
	v_fmaak_f32 v162, v161, v162, 0xbec09330
	v_fmaak_f32 v161, v161, v162, 0x3e0375d0
	v_fma_f32 v165, |v160|, v161, |v160|
	v_fma_f32 v161, |v160|, s72, v9
	v_fma_f32 v161, |v160|, v161, s73
	v_fma_f32 v161, |v160|, v161, s74
	v_fma_f32 v161, |v160|, v161, s75
	v_fma_f32 v161, |v160|, v161, s76
	v_fma_f32 v161, |v160|, v161, s77
	v_fma_f32 v161, |v160|, v161, |v160|
	v_mul_f32_e32 v162, 0xbfb8aa3b, v161
	v_fma_f32 v163, v161, s78, -v162
	v_rndne_f32_e32 v164, v162
	v_fmac_f32_e32 v163, 0xb2a5705f, v161
	v_sub_f32_e32 v162, v162, v164
	v_add_f32_e32 v162, v162, v163
	v_cvt_i32_f32_e32 v163, v164
	v_exp_f32_e32 v162, v162
	v_cmp_nlt_f32_e32 vcc, s79, v161
	v_ldexp_f32 v162, v162, v163
	s_nop 0
	v_cndmask_b32_e32 v162, 0, v162, vcc
	v_cmp_ngt_f32_e32 vcc, s80, v161
	s_nop 1
	v_cndmask_b32_e32 v161, v3, v162, vcc
	v_sub_f32_e32 v166, 1.0, v161
	v_cmp_lt_f32_e64 vcc, |v160|, 1.0
	s_nop 1
	v_cndmask_b32_e32 v165, v166, v165, vcc
	v_bfi_b32 v165, s81, v165, v160
	v_mul_f32_e32 v161, 0.5, v169
	v_add_f32_e32 v165, 1.0, v165
	v_mul_f32_e32 v161, v161, v165
	v_mul_f32_e32 v177, v161, v5
	v_mul_f32_e32 v160, 0x3f3504f3, v170
	v_mul_f32_e32 v161, v160, v160
	v_fmamk_f32 v162, v161, 0xba1345e1, v8
	v_fmaak_f32 v162, v161, v162, 0xbcdac9b8
	v_fmaak_f32 v162, v161, v162, 0x3de703be
	v_fmaak_f32 v162, v161, v162, 0xbec09330
	v_fmaak_f32 v161, v161, v162, 0x3e0375d0
	v_fma_f32 v165, |v160|, v161, |v160|
	v_fma_f32 v161, |v160|, s72, v9
	v_fma_f32 v161, |v160|, v161, s73
	v_fma_f32 v161, |v160|, v161, s74
	v_fma_f32 v161, |v160|, v161, s75
	v_fma_f32 v161, |v160|, v161, s76
	v_fma_f32 v161, |v160|, v161, s77
	v_fma_f32 v161, |v160|, v161, |v160|
	v_mul_f32_e32 v162, 0xbfb8aa3b, v161
	v_fma_f32 v163, v161, s78, -v162
	v_rndne_f32_e32 v164, v162
	v_fmac_f32_e32 v163, 0xb2a5705f, v161
	v_sub_f32_e32 v162, v162, v164
; DEV unsigned pack2(float a, float b) { float2v v = {a, b}; return __builtin_bit_cast(unsigned, __builtin_convertvector(v, bf16x2v)); }
; DEV float bflo(unsigned u) { return __uint_as_float(u << 16); }
; DEV float bfhi(unsigned u) { return __uint_as_float(u & 0xffff0000u); }
; DEV float gelu_exact(float v) { return 0.5f * v * (1.f + erff(v * 0.7071067811865476f)); }
; DEV void ph_scan2(const Params& p, int item) {
;     ...
;   for (int t = 0; t < CHL; ++t) {
;     float4 a = *(const float4*)(p.a_arr + (row0 + t) * 1024 + ch);
;     float4 bb = *(const float4*)(p.b_arr + (row0 + t) * 1024 + ch);
;     u32x2 xg = *(const u32x2*)(p.z + (row0 + t) * ZLD + CXG + ch);
;     H[0] = a.x * H[0] + bb.x; H[1] = a.y * H[1] + bb.y; H[2] = a.z * H[2] + bb.z; H[3] = a.w * H[3] + bb.w;
;     u32x2 pk;
;     pk[0] = pack2(gelu_exact(bflo(xg[0])) * H[0], gelu_exact(bfhi(xg[0])) * H[1]);
;     pk[1] = pack2(gelu_exact(bflo(xg[1])) * H[2], gelu_exact(bfhi(xg[1])) * H[3]);
;     *(u32x2*)(p.orn + (row0 + t) * 1024 + ch) = pk;
;   }
	v_add_f32_e32 v162, v162, v163
	v_cvt_i32_f32_e32 v163, v164
	v_exp_f32_e32 v162, v162
	v_cmp_nlt_f32_e32 vcc, s79, v161
	v_ldexp_f32 v162, v162, v163
	s_nop 0
	v_cndmask_b32_e32 v162, 0, v162, vcc
	v_cmp_ngt_f32_e32 vcc, s80, v161
	s_nop 1
	v_cndmask_b32_e32 v161, v3, v162, vcc
	v_sub_f32_e32 v166, 1.0, v161
	v_cmp_lt_f32_e64 vcc, |v160|, 1.0
	s_nop 1
	v_cndmask_b32_e32 v165, v166, v165, vcc
	v_bfi_b32 v165, s81, v165, v160
	v_mul_f32_e32 v161, 0.5, v170
	v_add_f32_e32 v165, 1.0, v165
	v_mul_f32_e32 v161, v161, v165
	v_mul_f32_e32 v178, v161, v6
	v_mul_f32_e32 v160, 0x3f3504f3, v171
	v_mul_f32_e32 v161, v160, v160
	v_fmamk_f32 v162, v161, 0xba1345e1, v8
	v_fmaak_f32 v162, v161, v162, 0xbcdac9b8
	v_fmaak_f32 v162, v161, v162, 0x3de703be
	v_fmaak_f32 v162, v161, v162, 0xbec09330
	v_fmaak_f32 v161, v161, v162, 0x3e0375d0
	v_fma_f32 v165, |v160|, v161, |v160|
	v_fma_f32 v161, |v160|, s72, v9
	v_fma_f32 v161, |v160|, v161, s73
	v_fma_f32 v161, |v160|, v161, s74
	v_fma_f32 v161, |v160|, v161, s75
	v_fma_f32 v161, |v160|, v161, s76
	v_fma_f32 v161, |v160|, v161, s77
	v_fma_f32 v161, |v160|, v161, |v160|
	v_mul_f32_e32 v162, 0xbfb8aa3b, v161
	v_fma_f32 v163, v161, s78, -v162
	v_rndne_f32_e32 v164, v162
	v_fmac_f32_e32 v163, 0xb2a5705f, v161
	v_sub_f32_e32 v162, v162, v164
	v_add_f32_e32 v162, v162, v163
	v_cvt_i32_f32_e32 v163, v164
	v_exp_f32_e32 v162, v162
	v_cmp_nlt_f32_e32 vcc, s79, v161
	v_ldexp_f32 v162, v162, v163
	s_nop 0
	v_cndmask_b32_e32 v162, 0, v162, vcc
	v_cmp_ngt_f32_e32 vcc, s80, v161
	s_nop 1
	v_cndmask_b32_e32 v161, v3, v162, vcc
	v_sub_f32_e32 v166, 1.0, v161
	v_cmp_lt_f32_e64 vcc, |v160|, 1.0
	s_nop 1
	v_cndmask_b32_e32 v165, v166, v165, vcc
	v_bfi_b32 v165, s81, v165, v160
	v_mul_f32_e32 v161, 0.5, v171
	v_add_f32_e32 v165, 1.0, v165
	v_mul_f32_e32 v161, v161, v165
	v_mul_f32_e32 v179, v161, v7
	v_cvt_pk_bf16_f32 v180, v176, v177
	v_cvt_pk_bf16_f32 v181, v178, v179
	global_store_dwordx2 v2, v[180:181], s[34:35]
	s_add_u32 s34, s34, 0x800
	s_addc_u32 s35, s35, 0
	s_waitcnt vmcnt(13)
	v_fma_f32 v4, v120, v4, v124
	v_fma_f32 v5, v121, v5, v125
	v_fma_f32 v6, v122, v6, v126
	v_fma_f32 v7, v123, v7, v127
	v_lshlrev_b32_e32 v168, 16, v128
	v_and_b32_e32 v169, 0xffff0000, v128
	v_lshlrev_b32_e32 v170, 16, v129
	v_and_b32_e32 v171, 0xffff0000, v129
	v_mul_f32_e32 v160, 0x3f3504f3, v168
	v_mul_f32_e32 v161, v160, v160
	v_fmamk_f32 v162, v161, 0xba1345e1, v8
	v_fmaak_f32 v162, v161, v162, 0xbcdac9b8
	v_fmaak_f32 v162, v161, v162, 0x3de703be
	v_fmaak_f32 v162, v161, v162, 0xbec09330
	v_fmaak_f32 v161, v161, v162, 0x3e0375d0
	v_fma_f32 v165, |v160|, v161, |v160|
	v_fma_f32 v161, |v160|, s72, v9
	v_fma_f32 v161, |v160|, v161, s73
	v_fma_f32 v161, |v160|, v161, s74
	v_fma_f32 v161, |v160|, v161, s75
	v_fma_f32 v161, |v160|, v161, s76
	v_fma_f32 v161, |v160|, v161, s77
	v_fma_f32 v161, |v160|, v161, |v160|
	v_mul_f32_e32 v162, 0xbfb8aa3b, v161
	v_fma_f32 v163, v161, s78, -v162
	v_rndne_f32_e32 v164, v162
	v_fmac_f32_e32 v163, 0xb2a5705f, v161
	v_sub_f32_e32 v162, v162, v164
	v_add_f32_e32 v162, v162, v163
	v_cvt_i32_f32_e32 v163, v164
	v_exp_f32_e32 v162, v162
	v_cmp_nlt_f32_e32 vcc, s79, v161
	v_ldexp_f32 v162, v162, v163
	s_nop 0
	v_cndmask_b32_e32 v162, 0, v162, vcc
	v_cmp_ngt_f32_e32 vcc, s80, v161
	s_nop 1
	v_cndmask_b32_e32 v161, v3, v162, vcc
	v_sub_f32_e32 v166, 1.0, v161
	v_cmp_lt_f32_e64 vcc, |v160|, 1.0
	s_nop 1
	v_cndmask_b32_e32 v165, v166, v165, vcc
	v_bfi_b32 v165, s81, v165, v160
	v_mul_f32_e32 v161, 0.5, v168
	v_add_f32_e32 v165, 1.0, v165
	v_mul_f32_e32 v161, v161, v165
	v_mul_f32_e32 v176, v161, v4
	v_mul_f32_e32 v160, 0x3f3504f3, v169
	v_mul_f32_e32 v161, v160, v160
	v_fmamk_f32 v162, v161, 0xba1345e1, v8
	v_fmaak_f32 v162, v161, v162, 0xbcdac9b8
	v_fmaak_f32 v162, v161, v162, 0x3de703be
	v_fmaak_f32 v162, v161, v162, 0xbec09330
	v_fmaak_f32 v161, v161, v162, 0x3e0375d0
	v_fma_f32 v165, |v160|, v161, |v160|
	v_fma_f32 v161, |v160|, s72, v9
	v_fma_f32 v161, |v160|, v161, s73
	v_fma_f32 v161, |v160|, v161, s74
	v_fma_f32 v161, |v160|, v161, s75
	v_fma_f32 v161, |v160|, v161, s76
	v_fma_f32 v161, |v160|, v161, s77
	v_fma_f32 v161, |v160|, v161, |v160|
	v_mul_f32_e32 v162, 0xbfb8aa3b, v161
	v_fma_f32 v163, v161, s78, -v162
	v_rndne_f32_e32 v164, v162
	v_fmac_f32_e32 v163, 0xb2a5705f, v161
	v_sub_f32_e32 v162, v162, v164
	v_add_f32_e32 v162, v162, v163
	v_cvt_i32_f32_e32 v163, v164
	v_exp_f32_e32 v162, v162
	v_cmp_nlt_f32_e32 vcc, s79, v161
	v_ldexp_f32 v162, v162, v163
	s_nop 0
	v_cndmask_b32_e32 v162, 0, v162, vcc
	v_cmp_ngt_f32_e32 vcc, s80, v161
	s_nop 1
	v_cndmask_b32_e32 v161, v3, v162, vcc
	v_sub_f32_e32 v166, 1.0, v161
	v_cmp_lt_f32_e64 vcc, |v160|, 1.0
	s_nop 1
	v_cndmask_b32_e32 v165, v166, v165, vcc
	v_bfi_b32 v165, s81, v165, v160
	v_mul_f32_e32 v161, 0.5, v169
	v_add_f32_e32 v165, 1.0, v165
	v_mul_f32_e32 v161, v161, v165
	v_mul_f32_e32 v177, v161, v5
	v_mul_f32_e32 v160, 0x3f3504f3, v170
	v_mul_f32_e32 v161, v160, v160
	v_fmamk_f32 v162, v161, 0xba1345e1, v8
	v_fmaak_f32 v162, v161, v162, 0xbcdac9b8
	v_fmaak_f32 v162, v161, v162, 0x3de703be
	v_fmaak_f32 v162, v161, v162, 0xbec09330
	v_fmaak_f32 v161, v161, v162, 0x3e0375d0
	v_fma_f32 v165, |v160|, v161, |v160|
	v_fma_f32 v161, |v160|, s72, v9
	v_fma_f32 v161, |v160|, v161, s73
	v_fma_f32 v161, |v160|, v161, s74
	v_fma_f32 v161, |v160|, v161, s75
	v_fma_f32 v161, |v160|, v161, s76
	v_fma_f32 v161, |v160|, v161, s77
	v_fma_f32 v161, |v160|, v161, |v160|
	v_mul_f32_e32 v162, 0xbfb8aa3b, v161
	v_fma_f32 v163, v161, s78, -v162
	v_rndne_f32_e32 v164, v162
	v_fmac_f32_e32 v163, 0xb2a5705f, v161
	v_sub_f32_e32 v162, v162, v164
	v_add_f32_e32 v162, v162, v163
; DEV unsigned pack2(float a, float b) { float2v v = {a, b}; return __builtin_bit_cast(unsigned, __builtin_convertvector(v, bf16x2v)); }
; DEV float bflo(unsigned u) { return __uint_as_float(u << 16); }
; DEV float bfhi(unsigned u) { return __uint_as_float(u & 0xffff0000u); }
; DEV float gelu_exact(float v) { return 0.5f * v * (1.f + erff(v * 0.7071067811865476f)); }
; DEV void ph_scan2(const Params& p, int item) {
;     ...
;   for (int t = 0; t < CHL; ++t) {
;     float4 a = *(const float4*)(p.a_arr + (row0 + t) * 1024 + ch);
;     float4 bb = *(const float4*)(p.b_arr + (row0 + t) * 1024 + ch);
;     u32x2 xg = *(const u32x2*)(p.z + (row0 + t) * ZLD + CXG + ch);
;     H[0] = a.x * H[0] + bb.x; H[1] = a.y * H[1] + bb.y; H[2] = a.z * H[2] + bb.z; H[3] = a.w * H[3] + bb.w;
;     u32x2 pk;
;     pk[0] = pack2(gelu_exact(bflo(xg[0])) * H[0], gelu_exact(bfhi(xg[0])) * H[1]);
;     pk[1] = pack2(gelu_exact(bflo(xg[1])) * H[2], gelu_exact(bfhi(xg[1])) * H[3]);
;     *(u32x2*)(p.orn + (row0 + t) * 1024 + ch) = pk;
;   }
	v_cvt_i32_f32_e32 v163, v164
	v_exp_f32_e32 v162, v162
	v_cmp_nlt_f32_e32 vcc, s79, v161
	v_ldexp_f32 v162, v162, v163
	s_nop 0
	v_cndmask_b32_e32 v162, 0, v162, vcc
	v_cmp_ngt_f32_e32 vcc, s80, v161
	s_nop 1
	v_cndmask_b32_e32 v161, v3, v162, vcc
	v_sub_f32_e32 v166, 1.0, v161
	v_cmp_lt_f32_e64 vcc, |v160|, 1.0
	s_nop 1
	v_cndmask_b32_e32 v165, v166, v165, vcc
	v_bfi_b32 v165, s81, v165, v160
	v_mul_f32_e32 v161, 0.5, v170
	v_add_f32_e32 v165, 1.0, v165
	v_mul_f32_e32 v161, v161, v165
	v_mul_f32_e32 v178, v161, v6
	v_mul_f32_e32 v160, 0x3f3504f3, v171
	v_mul_f32_e32 v161, v160, v160
	v_fmamk_f32 v162, v161, 0xba1345e1, v8
	v_fmaak_f32 v162, v161, v162, 0xbcdac9b8
	v_fmaak_f32 v162, v161, v162, 0x3de703be
	v_fmaak_f32 v162, v161, v162, 0xbec09330
	v_fmaak_f32 v161, v161, v162, 0x3e0375d0
	v_fma_f32 v165, |v160|, v161, |v160|
	v_fma_f32 v161, |v160|, s72, v9
	v_fma_f32 v161, |v160|, v161, s73
	v_fma_f32 v161, |v160|, v161, s74
	v_fma_f32 v161, |v160|, v161, s75
	v_fma_f32 v161, |v160|, v161, s76
	v_fma_f32 v161, |v160|, v161, s77
	v_fma_f32 v161, |v160|, v161, |v160|
	v_mul_f32_e32 v162, 0xbfb8aa3b, v161
	v_fma_f32 v163, v161, s78, -v162
	v_rndne_f32_e32 v164, v162
	v_fmac_f32_e32 v163, 0xb2a5705f, v161
	v_sub_f32_e32 v162, v162, v164
	v_add_f32_e32 v162, v162, v163
	v_cvt_i32_f32_e32 v163, v164
	v_exp_f32_e32 v162, v162
	v_cmp_nlt_f32_e32 vcc, s79, v161
	v_ldexp_f32 v162, v162, v163
	s_nop 0
	v_cndmask_b32_e32 v162, 0, v162, vcc
	v_cmp_ngt_f32_e32 vcc, s80, v161
	s_nop 1
	v_cndmask_b32_e32 v161, v3, v162, vcc
	v_sub_f32_e32 v166, 1.0, v161
	v_cmp_lt_f32_e64 vcc, |v160|, 1.0
	s_nop 1
	v_cndmask_b32_e32 v165, v166, v165, vcc
	v_bfi_b32 v165, s81, v165, v160
	v_mul_f32_e32 v161, 0.5, v171
	v_add_f32_e32 v165, 1.0, v165
	v_mul_f32_e32 v161, v161, v165
	v_mul_f32_e32 v179, v161, v7
	v_cvt_pk_bf16_f32 v180, v176, v177
	v_cvt_pk_bf16_f32 v181, v178, v179
	global_store_dwordx2 v2, v[180:181], s[34:35]
	s_add_u32 s34, s34, 0x800
	s_addc_u32 s35, s35, 0
	s_waitcnt vmcnt(11)
	v_fma_f32 v4, v130, v4, v134
	v_fma_f32 v5, v131, v5, v135
	v_fma_f32 v6, v132, v6, v136
	v_fma_f32 v7, v133, v7, v137
	v_lshlrev_b32_e32 v168, 16, v138
	v_and_b32_e32 v169, 0xffff0000, v138
	v_lshlrev_b32_e32 v170, 16, v139
	v_and_b32_e32 v171, 0xffff0000, v139
	v_mul_f32_e32 v160, 0x3f3504f3, v168
	v_mul_f32_e32 v161, v160, v160
	v_fmamk_f32 v162, v161, 0xba1345e1, v8
	v_fmaak_f32 v162, v161, v162, 0xbcdac9b8
	v_fmaak_f32 v162, v161, v162, 0x3de703be
	v_fmaak_f32 v162, v161, v162, 0xbec09330
	v_fmaak_f32 v161, v161, v162, 0x3e0375d0
	v_fma_f32 v165, |v160|, v161, |v160|
	v_fma_f32 v161, |v160|, s72, v9
	v_fma_f32 v161, |v160|, v161, s73
	v_fma_f32 v161, |v160|, v161, s74
	v_fma_f32 v161, |v160|, v161, s75
	v_fma_f32 v161, |v160|, v161, s76
	v_fma_f32 v161, |v160|, v161, s77
	v_fma_f32 v161, |v160|, v161, |v160|
	v_mul_f32_e32 v162, 0xbfb8aa3b, v161
	v_fma_f32 v163, v161, s78, -v162
	v_rndne_f32_e32 v164, v162
	v_fmac_f32_e32 v163, 0xb2a5705f, v161
	v_sub_f32_e32 v162, v162, v164
	v_add_f32_e32 v162, v162, v163
	v_cvt_i32_f32_e32 v163, v164
	v_exp_f32_e32 v162, v162
	v_cmp_nlt_f32_e32 vcc, s79, v161
	v_ldexp_f32 v162, v162, v163
	s_nop 0
	v_cndmask_b32_e32 v162, 0, v162, vcc
	v_cmp_ngt_f32_e32 vcc, s80, v161
	s_nop 1
	v_cndmask_b32_e32 v161, v3, v162, vcc
	v_sub_f32_e32 v166, 1.0, v161
	v_cmp_lt_f32_e64 vcc, |v160|, 1.0
	s_nop 1
	v_cndmask_b32_e32 v165, v166, v165, vcc
	v_bfi_b32 v165, s81, v165, v160
	v_mul_f32_e32 v161, 0.5, v168
	v_add_f32_e32 v165, 1.0, v165
	v_mul_f32_e32 v161, v161, v165
	v_mul_f32_e32 v176, v161, v4
	v_mul_f32_e32 v160, 0x3f3504f3, v169
	v_mul_f32_e32 v161, v160, v160
	v_fmamk_f32 v162, v161, 0xba1345e1, v8
	v_fmaak_f32 v162, v161, v162, 0xbcdac9b8
	v_fmaak_f32 v162, v161, v162, 0x3de703be
	v_fmaak_f32 v162, v161, v162, 0xbec09330
	v_fmaak_f32 v161, v161, v162, 0x3e0375d0
	v_fma_f32 v165, |v160|, v161, |v160|
	v_fma_f32 v161, |v160|, s72, v9
	v_fma_f32 v161, |v160|, v161, s73
	v_fma_f32 v161, |v160|, v161, s74
	v_fma_f32 v161, |v160|, v161, s75
	v_fma_f32 v161, |v160|, v161, s76
	v_fma_f32 v161, |v160|, v161, s77
	v_fma_f32 v161, |v160|, v161, |v160|
	v_mul_f32_e32 v162, 0xbfb8aa3b, v161
	v_fma_f32 v163, v161, s78, -v162
	v_rndne_f32_e32 v164, v162
	v_fmac_f32_e32 v163, 0xb2a5705f, v161
	v_sub_f32_e32 v162, v162, v164
	v_add_f32_e32 v162, v162, v163
	v_cvt_i32_f32_e32 v163, v164
	v_exp_f32_e32 v162, v162
	v_cmp_nlt_f32_e32 vcc, s79, v161
	v_ldexp_f32 v162, v162, v163
	s_nop 0
	v_cndmask_b32_e32 v162, 0, v162, vcc
	v_cmp_ngt_f32_e32 vcc, s80, v161
	s_nop 1
	v_cndmask_b32_e32 v161, v3, v162, vcc
	v_sub_f32_e32 v166, 1.0, v161
	v_cmp_lt_f32_e64 vcc, |v160|, 1.0
	s_nop 1
	v_cndmask_b32_e32 v165, v166, v165, vcc
	v_bfi_b32 v165, s81, v165, v160
	v_mul_f32_e32 v161, 0.5, v169
	v_add_f32_e32 v165, 1.0, v165
	v_mul_f32_e32 v161, v161, v165
	v_mul_f32_e32 v177, v161, v5
	v_mul_f32_e32 v160, 0x3f3504f3, v170
	v_mul_f32_e32 v161, v160, v160
	v_fmamk_f32 v162, v161, 0xba1345e1, v8
	v_fmaak_f32 v162, v161, v162, 0xbcdac9b8
	v_fmaak_f32 v162, v161, v162, 0x3de703be
	v_fmaak_f32 v162, v161, v162, 0xbec09330
	v_fmaak_f32 v161, v161, v162, 0x3e0375d0
	v_fma_f32 v165, |v160|, v161, |v160|
	v_fma_f32 v161, |v160|, s72, v9
	v_fma_f32 v161, |v160|, v161, s73
	v_fma_f32 v161, |v160|, v161, s74
	v_fma_f32 v161, |v160|, v161, s75
	v_fma_f32 v161, |v160|, v161, s76
	v_fma_f32 v161, |v160|, v161, s77
	v_fma_f32 v161, |v160|, v161, |v160|
	v_mul_f32_e32 v162, 0xbfb8aa3b, v161
	v_fma_f32 v163, v161, s78, -v162
	v_rndne_f32_e32 v164, v162
	v_fmac_f32_e32 v163, 0xb2a5705f, v161
	v_sub_f32_e32 v162, v162, v164
	v_add_f32_e32 v162, v162, v163
	v_cvt_i32_f32_e32 v163, v164
; DEV unsigned pack2(float a, float b) { float2v v = {a, b}; return __builtin_bit_cast(unsigned, __builtin_convertvector(v, bf16x2v)); }
; DEV float bflo(unsigned u) { return __uint_as_float(u << 16); }
; DEV float bfhi(unsigned u) { return __uint_as_float(u & 0xffff0000u); }
; DEV float gelu_exact(float v) { return 0.5f * v * (1.f + erff(v * 0.7071067811865476f)); }
; DEV void ph_scan2(const Params& p, int item) {
;     ...
;   for (int t = 0; t < CHL; ++t) {
;     float4 a = *(const float4*)(p.a_arr + (row0 + t) * 1024 + ch);
;     float4 bb = *(const float4*)(p.b_arr + (row0 + t) * 1024 + ch);
;     u32x2 xg = *(const u32x2*)(p.z + (row0 + t) * ZLD + CXG + ch);
;     H[0] = a.x * H[0] + bb.x; H[1] = a.y * H[1] + bb.y; H[2] = a.z * H[2] + bb.z; H[3] = a.w * H[3] + bb.w;
;     u32x2 pk;
;     pk[0] = pack2(gelu_exact(bflo(xg[0])) * H[0], gelu_exact(bfhi(xg[0])) * H[1]);
;     pk[1] = pack2(gelu_exact(bflo(xg[1])) * H[2], gelu_exact(bfhi(xg[1])) * H[3]);
;     *(u32x2*)(p.orn + (row0 + t) * 1024 + ch) = pk;
;   }
	v_exp_f32_e32 v162, v162
	v_cmp_nlt_f32_e32 vcc, s79, v161
	v_ldexp_f32 v162, v162, v163
	s_nop 0
	v_cndmask_b32_e32 v162, 0, v162, vcc
	v_cmp_ngt_f32_e32 vcc, s80, v161
	s_nop 1
	v_cndmask_b32_e32 v161, v3, v162, vcc
	v_sub_f32_e32 v166, 1.0, v161
	v_cmp_lt_f32_e64 vcc, |v160|, 1.0
	s_nop 1
	v_cndmask_b32_e32 v165, v166, v165, vcc
	v_bfi_b32 v165, s81, v165, v160
	v_mul_f32_e32 v161, 0.5, v170
	v_add_f32_e32 v165, 1.0, v165
	v_mul_f32_e32 v161, v161, v165
	v_mul_f32_e32 v178, v161, v6
	v_mul_f32_e32 v160, 0x3f3504f3, v171
	v_mul_f32_e32 v161, v160, v160
	v_fmamk_f32 v162, v161, 0xba1345e1, v8
	v_fmaak_f32 v162, v161, v162, 0xbcdac9b8
	v_fmaak_f32 v162, v161, v162, 0x3de703be
	v_fmaak_f32 v162, v161, v162, 0xbec09330
	v_fmaak_f32 v161, v161, v162, 0x3e0375d0
	v_fma_f32 v165, |v160|, v161, |v160|
	v_fma_f32 v161, |v160|, s72, v9
	v_fma_f32 v161, |v160|, v161, s73
	v_fma_f32 v161, |v160|, v161, s74
	v_fma_f32 v161, |v160|, v161, s75
	v_fma_f32 v161, |v160|, v161, s76
	v_fma_f32 v161, |v160|, v161, s77
	v_fma_f32 v161, |v160|, v161, |v160|
	v_mul_f32_e32 v162, 0xbfb8aa3b, v161
	v_fma_f32 v163, v161, s78, -v162
	v_rndne_f32_e32 v164, v162
	v_fmac_f32_e32 v163, 0xb2a5705f, v161
	v_sub_f32_e32 v162, v162, v164
	v_add_f32_e32 v162, v162, v163
	v_cvt_i32_f32_e32 v163, v164
	v_exp_f32_e32 v162, v162
	v_cmp_nlt_f32_e32 vcc, s79, v161
	v_ldexp_f32 v162, v162, v163
	s_nop 0
	v_cndmask_b32_e32 v162, 0, v162, vcc
	v_cmp_ngt_f32_e32 vcc, s80, v161
	s_nop 1
	v_cndmask_b32_e32 v161, v3, v162, vcc
	v_sub_f32_e32 v166, 1.0, v161
	v_cmp_lt_f32_e64 vcc, |v160|, 1.0
	s_nop 1
	v_cndmask_b32_e32 v165, v166, v165, vcc
	v_bfi_b32 v165, s81, v165, v160
	v_mul_f32_e32 v161, 0.5, v171
	v_add_f32_e32 v165, 1.0, v165
	v_mul_f32_e32 v161, v161, v165
	v_mul_f32_e32 v179, v161, v7
	v_cvt_pk_bf16_f32 v180, v176, v177
	v_cvt_pk_bf16_f32 v181, v178, v179
	global_store_dwordx2 v2, v[180:181], s[34:35]
	s_add_u32 s34, s34, 0x800
	s_addc_u32 s35, s35, 0
	s_waitcnt vmcnt(9)
	v_fma_f32 v4, v140, v4, v144
	v_fma_f32 v5, v141, v5, v145
	v_fma_f32 v6, v142, v6, v146
	v_fma_f32 v7, v143, v7, v147
	v_lshlrev_b32_e32 v168, 16, v148
	v_and_b32_e32 v169, 0xffff0000, v148
	v_lshlrev_b32_e32 v170, 16, v149
	v_and_b32_e32 v171, 0xffff0000, v149
	v_mul_f32_e32 v160, 0x3f3504f3, v168
	v_mul_f32_e32 v161, v160, v160
	v_fmamk_f32 v162, v161, 0xba1345e1, v8
	v_fmaak_f32 v162, v161, v162, 0xbcdac9b8
	v_fmaak_f32 v162, v161, v162, 0x3de703be
	v_fmaak_f32 v162, v161, v162, 0xbec09330
	v_fmaak_f32 v161, v161, v162, 0x3e0375d0
	v_fma_f32 v165, |v160|, v161, |v160|
	v_fma_f32 v161, |v160|, s72, v9
	v_fma_f32 v161, |v160|, v161, s73
	v_fma_f32 v161, |v160|, v161, s74
	v_fma_f32 v161, |v160|, v161, s75
	v_fma_f32 v161, |v160|, v161, s76
	v_fma_f32 v161, |v160|, v161, s77
	v_fma_f32 v161, |v160|, v161, |v160|
	v_mul_f32_e32 v162, 0xbfb8aa3b, v161
	v_fma_f32 v163, v161, s78, -v162
	v_rndne_f32_e32 v164, v162
	v_fmac_f32_e32 v163, 0xb2a5705f, v161
	v_sub_f32_e32 v162, v162, v164
	v_add_f32_e32 v162, v162, v163
	v_cvt_i32_f32_e32 v163, v164
	v_exp_f32_e32 v162, v162
	v_cmp_nlt_f32_e32 vcc, s79, v161
	v_ldexp_f32 v162, v162, v163
	s_nop 0
	v_cndmask_b32_e32 v162, 0, v162, vcc
	v_cmp_ngt_f32_e32 vcc, s80, v161
	s_nop 1
	v_cndmask_b32_e32 v161, v3, v162, vcc
	v_sub_f32_e32 v166, 1.0, v161
	v_cmp_lt_f32_e64 vcc, |v160|, 1.0
	s_nop 1
	v_cndmask_b32_e32 v165, v166, v165, vcc
	v_bfi_b32 v165, s81, v165, v160
	v_mul_f32_e32 v161, 0.5, v168
	v_add_f32_e32 v165, 1.0, v165
	v_mul_f32_e32 v161, v161, v165
	v_mul_f32_e32 v176, v161, v4
	v_mul_f32_e32 v160, 0x3f3504f3, v169
	v_mul_f32_e32 v161, v160, v160
	v_fmamk_f32 v162, v161, 0xba1345e1, v8
	v_fmaak_f32 v162, v161, v162, 0xbcdac9b8
	v_fmaak_f32 v162, v161, v162, 0x3de703be
	v_fmaak_f32 v162, v161, v162, 0xbec09330
	v_fmaak_f32 v161, v161, v162, 0x3e0375d0
	v_fma_f32 v165, |v160|, v161, |v160|
	v_fma_f32 v161, |v160|, s72, v9
	v_fma_f32 v161, |v160|, v161, s73
	v_fma_f32 v161, |v160|, v161, s74
	v_fma_f32 v161, |v160|, v161, s75
	v_fma_f32 v161, |v160|, v161, s76
	v_fma_f32 v161, |v160|, v161, s77
	v_fma_f32 v161, |v160|, v161, |v160|
	v_mul_f32_e32 v162, 0xbfb8aa3b, v161
	v_fma_f32 v163, v161, s78, -v162
	v_rndne_f32_e32 v164, v162
	v_fmac_f32_e32 v163, 0xb2a5705f, v161
	v_sub_f32_e32 v162, v162, v164
	v_add_f32_e32 v162, v162, v163
	v_cvt_i32_f32_e32 v163, v164
	v_exp_f32_e32 v162, v162
	v_cmp_nlt_f32_e32 vcc, s79, v161
	v_ldexp_f32 v162, v162, v163
	s_nop 0
	v_cndmask_b32_e32 v162, 0, v162, vcc
	v_cmp_ngt_f32_e32 vcc, s80, v161
	s_nop 1
	v_cndmask_b32_e32 v161, v3, v162, vcc
	v_sub_f32_e32 v166, 1.0, v161
	v_cmp_lt_f32_e64 vcc, |v160|, 1.0
	s_nop 1
	v_cndmask_b32_e32 v165, v166, v165, vcc
	v_bfi_b32 v165, s81, v165, v160
	v_mul_f32_e32 v161, 0.5, v169
	v_add_f32_e32 v165, 1.0, v165
	v_mul_f32_e32 v161, v161, v165
	v_mul_f32_e32 v177, v161, v5
	v_mul_f32_e32 v160, 0x3f3504f3, v170
	v_mul_f32_e32 v161, v160, v160
	v_fmamk_f32 v162, v161, 0xba1345e1, v8
	v_fmaak_f32 v162, v161, v162, 0xbcdac9b8
	v_fmaak_f32 v162, v161, v162, 0x3de703be
	v_fmaak_f32 v162, v161, v162, 0xbec09330
	v_fmaak_f32 v161, v161, v162, 0x3e0375d0
	v_fma_f32 v165, |v160|, v161, |v160|
	v_fma_f32 v161, |v160|, s72, v9
	v_fma_f32 v161, |v160|, v161, s73
	v_fma_f32 v161, |v160|, v161, s74
	v_fma_f32 v161, |v160|, v161, s75
	v_fma_f32 v161, |v160|, v161, s76
	v_fma_f32 v161, |v160|, v161, s77
	v_fma_f32 v161, |v160|, v161, |v160|
	v_mul_f32_e32 v162, 0xbfb8aa3b, v161
	v_fma_f32 v163, v161, s78, -v162
	v_rndne_f32_e32 v164, v162
	v_fmac_f32_e32 v163, 0xb2a5705f, v161
	v_sub_f32_e32 v162, v162, v164
	v_add_f32_e32 v162, v162, v163
	v_cvt_i32_f32_e32 v163, v164
	v_exp_f32_e32 v162, v162
; DEV unsigned pack2(float a, float b) { float2v v = {a, b}; return __builtin_bit_cast(unsigned, __builtin_convertvector(v, bf16x2v)); }
; DEV float bflo(unsigned u) { return __uint_as_float(u << 16); }
; DEV float bfhi(unsigned u) { return __uint_as_float(u & 0xffff0000u); }
; DEV float gelu_exact(float v) { return 0.5f * v * (1.f + erff(v * 0.7071067811865476f)); }
; DEV void ph_scan2(const Params& p, int item) {
;     ...
;   for (int t = 0; t < CHL; ++t) {
;     float4 a = *(const float4*)(p.a_arr + (row0 + t) * 1024 + ch);
;     float4 bb = *(const float4*)(p.b_arr + (row0 + t) * 1024 + ch);
;     u32x2 xg = *(const u32x2*)(p.z + (row0 + t) * ZLD + CXG + ch);
;     H[0] = a.x * H[0] + bb.x; H[1] = a.y * H[1] + bb.y; H[2] = a.z * H[2] + bb.z; H[3] = a.w * H[3] + bb.w;
;     u32x2 pk;
;     pk[0] = pack2(gelu_exact(bflo(xg[0])) * H[0], gelu_exact(bfhi(xg[0])) * H[1]);
;     pk[1] = pack2(gelu_exact(bflo(xg[1])) * H[2], gelu_exact(bfhi(xg[1])) * H[3]);
;     *(u32x2*)(p.orn + (row0 + t) * 1024 + ch) = pk;
;   }
	v_cmp_nlt_f32_e32 vcc, s79, v161
	v_ldexp_f32 v162, v162, v163
	s_nop 0
	v_cndmask_b32_e32 v162, 0, v162, vcc
	v_cmp_ngt_f32_e32 vcc, s80, v161
	s_nop 1
	v_cndmask_b32_e32 v161, v3, v162, vcc
	v_sub_f32_e32 v166, 1.0, v161
	v_cmp_lt_f32_e64 vcc, |v160|, 1.0
	s_nop 1
	v_cndmask_b32_e32 v165, v166, v165, vcc
	v_bfi_b32 v165, s81, v165, v160
	v_mul_f32_e32 v161, 0.5, v170
	v_add_f32_e32 v165, 1.0, v165
	v_mul_f32_e32 v161, v161, v165
	v_mul_f32_e32 v178, v161, v6
	v_mul_f32_e32 v160, 0x3f3504f3, v171
	v_mul_f32_e32 v161, v160, v160
	v_fmamk_f32 v162, v161, 0xba1345e1, v8
	v_fmaak_f32 v162, v161, v162, 0xbcdac9b8
	v_fmaak_f32 v162, v161, v162, 0x3de703be
	v_fmaak_f32 v162, v161, v162, 0xbec09330
	v_fmaak_f32 v161, v161, v162, 0x3e0375d0
	v_fma_f32 v165, |v160|, v161, |v160|
	v_fma_f32 v161, |v160|, s72, v9
	v_fma_f32 v161, |v160|, v161, s73
	v_fma_f32 v161, |v160|, v161, s74
	v_fma_f32 v161, |v160|, v161, s75
	v_fma_f32 v161, |v160|, v161, s76
	v_fma_f32 v161, |v160|, v161, s77
	v_fma_f32 v161, |v160|, v161, |v160|
	v_mul_f32_e32 v162, 0xbfb8aa3b, v161
	v_fma_f32 v163, v161, s78, -v162
	v_rndne_f32_e32 v164, v162
	v_fmac_f32_e32 v163, 0xb2a5705f, v161
	v_sub_f32_e32 v162, v162, v164
	v_add_f32_e32 v162, v162, v163
	v_cvt_i32_f32_e32 v163, v164
	v_exp_f32_e32 v162, v162
	v_cmp_nlt_f32_e32 vcc, s79, v161
	v_ldexp_f32 v162, v162, v163
	s_nop 0
	v_cndmask_b32_e32 v162, 0, v162, vcc
	v_cmp_ngt_f32_e32 vcc, s80, v161
	s_nop 1
	v_cndmask_b32_e32 v161, v3, v162, vcc
	v_sub_f32_e32 v166, 1.0, v161
	v_cmp_lt_f32_e64 vcc, |v160|, 1.0
	s_nop 1
	v_cndmask_b32_e32 v165, v166, v165, vcc
	v_bfi_b32 v165, s81, v165, v160
	v_mul_f32_e32 v161, 0.5, v171
	v_add_f32_e32 v165, 1.0, v165
	v_mul_f32_e32 v161, v161, v165
	v_mul_f32_e32 v179, v161, v7
	v_cvt_pk_bf16_f32 v180, v176, v177
	v_cvt_pk_bf16_f32 v181, v178, v179
	global_store_dwordx2 v2, v[180:181], s[34:35]
	s_add_u32 s34, s34, 0x800
	s_addc_u32 s35, s35, 0
	s_waitcnt vmcnt(7)
; DEV unsigned pack2(float a, float b) { float2v v = {a, b}; return __builtin_bit_cast(unsigned, __builtin_convertvector(v, bf16x2v)); }
; DEV float bflo(unsigned u) { return __uint_as_float(u << 16); }
; DEV float bfhi(unsigned u) { return __uint_as_float(u & 0xffff0000u); }
; DEV float gelu_exact(float v) { return 0.5f * v * (1.f + erff(v * 0.7071067811865476f)); }
; DEV void ph_scan2(const Params& p, int item) {
;     ...
;   for (int t = 0; t < CHL; ++t) {
;     float4 a = *(const float4*)(p.a_arr + (row0 + t) * 1024 + ch);
;     float4 bb = *(const float4*)(p.b_arr + (row0 + t) * 1024 + ch);
;     u32x2 xg = *(const u32x2*)(p.z + (row0 + t) * ZLD + CXG + ch);
;     H[0] = a.x * H[0] + bb.x; H[1] = a.y * H[1] + bb.y; H[2] = a.z * H[2] + bb.z; H[3] = a.w * H[3] + bb.w;
;     u32x2 pk;
;     pk[0] = pack2(gelu_exact(bflo(xg[0])) * H[0], gelu_exact(bfhi(xg[0])) * H[1]);
;     pk[1] = pack2(gelu_exact(bflo(xg[1])) * H[2], gelu_exact(bfhi(xg[1])) * H[3]);
;     *(u32x2*)(p.orn + (row0 + t) * 1024 + ch) = pk;
;   }
; __global__ void __launch_bounds__(256, 2) fwd_megakernel(Params p) {
;     ...
;   for (int it = bid; it < B_ * NCH; it += nb) ph_scan2(p, it);
	v_fma_f32 v4, v150, v4, v154
	v_fma_f32 v5, v151, v5, v155
	v_fma_f32 v6, v152, v6, v156
	v_fma_f32 v7, v153, v7, v157
	v_lshlrev_b32_e32 v168, 16, v158
	v_and_b32_e32 v169, 0xffff0000, v158
	v_lshlrev_b32_e32 v170, 16, v159
	v_and_b32_e32 v171, 0xffff0000, v159
	v_mul_f32_e32 v160, 0x3f3504f3, v168
	v_mul_f32_e32 v161, v160, v160
	v_fmamk_f32 v162, v161, 0xba1345e1, v8
	v_fmaak_f32 v162, v161, v162, 0xbcdac9b8
	v_fmaak_f32 v162, v161, v162, 0x3de703be
	v_fmaak_f32 v162, v161, v162, 0xbec09330
	v_fmaak_f32 v161, v161, v162, 0x3e0375d0
	v_fma_f32 v165, |v160|, v161, |v160|
	v_fma_f32 v161, |v160|, s72, v9
	v_fma_f32 v161, |v160|, v161, s73
	v_fma_f32 v161, |v160|, v161, s74
	v_fma_f32 v161, |v160|, v161, s75
	v_fma_f32 v161, |v160|, v161, s76
	v_fma_f32 v161, |v160|, v161, s77
	v_fma_f32 v161, |v160|, v161, |v160|
	v_mul_f32_e32 v162, 0xbfb8aa3b, v161
	v_fma_f32 v163, v161, s78, -v162
	v_rndne_f32_e32 v164, v162
	v_fmac_f32_e32 v163, 0xb2a5705f, v161
	v_sub_f32_e32 v162, v162, v164
	v_add_f32_e32 v162, v162, v163
	v_cvt_i32_f32_e32 v163, v164
	v_exp_f32_e32 v162, v162
	v_cmp_nlt_f32_e32 vcc, s79, v161
	v_ldexp_f32 v162, v162, v163
	s_nop 0
	v_cndmask_b32_e32 v162, 0, v162, vcc
	v_cmp_ngt_f32_e32 vcc, s80, v161
	s_nop 1
	v_cndmask_b32_e32 v161, v3, v162, vcc
	v_sub_f32_e32 v166, 1.0, v161
	v_cmp_lt_f32_e64 vcc, |v160|, 1.0
	s_nop 1
	v_cndmask_b32_e32 v165, v166, v165, vcc
	v_bfi_b32 v165, s81, v165, v160
	v_mul_f32_e32 v161, 0.5, v168
	v_add_f32_e32 v165, 1.0, v165
	v_mul_f32_e32 v161, v161, v165
	v_mul_f32_e32 v176, v161, v4
	v_mul_f32_e32 v160, 0x3f3504f3, v169
	v_mul_f32_e32 v161, v160, v160
	v_fmamk_f32 v162, v161, 0xba1345e1, v8
	v_fmaak_f32 v162, v161, v162, 0xbcdac9b8
	v_fmaak_f32 v162, v161, v162, 0x3de703be
	v_fmaak_f32 v162, v161, v162, 0xbec09330
	v_fmaak_f32 v161, v161, v162, 0x3e0375d0
	v_fma_f32 v165, |v160|, v161, |v160|
	v_fma_f32 v161, |v160|, s72, v9
	v_fma_f32 v161, |v160|, v161, s73
	v_fma_f32 v161, |v160|, v161, s74
	v_fma_f32 v161, |v160|, v161, s75
	v_fma_f32 v161, |v160|, v161, s76
	v_fma_f32 v161, |v160|, v161, s77
	v_fma_f32 v161, |v160|, v161, |v160|
	v_mul_f32_e32 v162, 0xbfb8aa3b, v161
	v_fma_f32 v163, v161, s78, -v162
	v_rndne_f32_e32 v164, v162
	v_fmac_f32_e32 v163, 0xb2a5705f, v161
	v_sub_f32_e32 v162, v162, v164
	v_add_f32_e32 v162, v162, v163
	v_cvt_i32_f32_e32 v163, v164
	v_exp_f32_e32 v162, v162
	v_cmp_nlt_f32_e32 vcc, s79, v161
	v_ldexp_f32 v162, v162, v163
	s_nop 0
	v_cndmask_b32_e32 v162, 0, v162, vcc
	v_cmp_ngt_f32_e32 vcc, s80, v161
	s_nop 1
	v_cndmask_b32_e32 v161, v3, v162, vcc
	v_sub_f32_e32 v166, 1.0, v161
	v_cmp_lt_f32_e64 vcc, |v160|, 1.0
	s_nop 1
	v_cndmask_b32_e32 v165, v166, v165, vcc
	v_bfi_b32 v165, s81, v165, v160
	v_mul_f32_e32 v161, 0.5, v169
	v_add_f32_e32 v165, 1.0, v165
	v_mul_f32_e32 v161, v161, v165
	v_mul_f32_e32 v177, v161, v5
	v_mul_f32_e32 v160, 0x3f3504f3, v170
	v_mul_f32_e32 v161, v160, v160
	v_fmamk_f32 v162, v161, 0xba1345e1, v8
	v_fmaak_f32 v162, v161, v162, 0xbcdac9b8
	v_fmaak_f32 v162, v161, v162, 0x3de703be
	v_fmaak_f32 v162, v161, v162, 0xbec09330
	v_fmaak_f32 v161, v161, v162, 0x3e0375d0
	v_fma_f32 v165, |v160|, v161, |v160|
	v_fma_f32 v161, |v160|, s72, v9
	v_fma_f32 v161, |v160|, v161, s73
	v_fma_f32 v161, |v160|, v161, s74
	v_fma_f32 v161, |v160|, v161, s75
	v_fma_f32 v161, |v160|, v161, s76
	v_fma_f32 v161, |v160|, v161, s77
	v_fma_f32 v161, |v160|, v161, |v160|
	v_mul_f32_e32 v162, 0xbfb8aa3b, v161
	v_fma_f32 v163, v161, s78, -v162
	v_rndne_f32_e32 v164, v162
	v_fmac_f32_e32 v163, 0xb2a5705f, v161
	v_sub_f32_e32 v162, v162, v164
	v_add_f32_e32 v162, v162, v163
	v_cvt_i32_f32_e32 v163, v164
	v_exp_f32_e32 v162, v162
	v_cmp_nlt_f32_e32 vcc, s79, v161
	v_ldexp_f32 v162, v162, v163
	s_nop 0
	v_cndmask_b32_e32 v162, 0, v162, vcc
	v_cmp_ngt_f32_e32 vcc, s80, v161
	s_nop 1
	v_cndmask_b32_e32 v161, v3, v162, vcc
	v_sub_f32_e32 v166, 1.0, v161
	v_cmp_lt_f32_e64 vcc, |v160|, 1.0
	s_nop 1
	v_cndmask_b32_e32 v165, v166, v165, vcc
	v_bfi_b32 v165, s81, v165, v160
	v_mul_f32_e32 v161, 0.5, v170
	v_add_f32_e32 v165, 1.0, v165
	v_mul_f32_e32 v161, v161, v165
	v_mul_f32_e32 v178, v161, v6
	v_mul_f32_e32 v160, 0x3f3504f3, v171
	v_mul_f32_e32 v161, v160, v160
	v_fmamk_f32 v162, v161, 0xba1345e1, v8
	v_fmaak_f32 v162, v161, v162, 0xbcdac9b8
	v_fmaak_f32 v162, v161, v162, 0x3de703be
	v_fmaak_f32 v162, v161, v162, 0xbec09330
	v_fmaak_f32 v161, v161, v162, 0x3e0375d0
	v_fma_f32 v165, |v160|, v161, |v160|
	v_fma_f32 v161, |v160|, s72, v9
	v_fma_f32 v161, |v160|, v161, s73
	v_fma_f32 v161, |v160|, v161, s74
	v_fma_f32 v161, |v160|, v161, s75
	v_fma_f32 v161, |v160|, v161, s76
	v_fma_f32 v161, |v160|, v161, s77
	v_fma_f32 v161, |v160|, v161, |v160|
	v_mul_f32_e32 v162, 0xbfb8aa3b, v161
	v_fma_f32 v163, v161, s78, -v162
	v_rndne_f32_e32 v164, v162
	v_fmac_f32_e32 v163, 0xb2a5705f, v161
	v_sub_f32_e32 v162, v162, v164
	v_add_f32_e32 v162, v162, v163
	v_cvt_i32_f32_e32 v163, v164
	v_exp_f32_e32 v162, v162
	v_cmp_nlt_f32_e32 vcc, s79, v161
	v_ldexp_f32 v162, v162, v163
	s_nop 0
	v_cndmask_b32_e32 v162, 0, v162, vcc
	v_cmp_ngt_f32_e32 vcc, s80, v161
	s_nop 1
	v_cndmask_b32_e32 v161, v3, v162, vcc
	v_sub_f32_e32 v166, 1.0, v161
	v_cmp_lt_f32_e64 vcc, |v160|, 1.0
	s_nop 1
	v_cndmask_b32_e32 v165, v166, v165, vcc
	v_bfi_b32 v165, s81, v165, v160
	v_mul_f32_e32 v161, 0.5, v171
	v_add_f32_e32 v165, 1.0, v165
	v_mul_f32_e32 v161, v161, v165
	v_mul_f32_e32 v179, v161, v7
	v_cvt_pk_bf16_f32 v180, v176, v177
	v_cvt_pk_bf16_f32 v181, v178, v179
	global_store_dwordx2 v2, v[180:181], s[34:35]
	s_add_u32 s34, s34, 0x800
	s_addc_u32 s35, s35, 0
	s_add_u32 s41, s41, 1
	s_cmp_lt_u32 s41, 4
	s_cbranch_scc1 .Lsc_main
	s_add_i32 s50, s50, s92
	s_cmpk_lt_i32 s50, 0x200
	s_cbranch_scc1 .Lsc_item
	v_readlane_b32 s2, v254, 0
	s_nop 3
	s_cmp_lt_u32 s2, 0x100
	s_cbranch_scc1 .Lp5_resume
